# lean9 = lean7 + W_in epilogue row-statistic loads of all four row batches issued together at the epilogue head + gate-bias floats held in spare VGPRs
# baseline (speedup 1.0000x reference)
; #define PG8_STAGE(bufoff, gbase, voff) do { _Pragma("unroll") for (int _i = 0; _i < 2; ++_i) \
;         __builtin_amdgcn_global_load_lds((const unsigned*)((const char*)(gbase) + (voff)[_i]), (PG8_LAS unsigned*)(lds + (bufoff) + ldsw + _i * 8192), 16, 0, 0); } while (0)
; #define PG8_WAIT_V(n) asm volatile("s_waitcnt vmcnt(" #n ")" ::: "memory")
; #define PG8_BAR __builtin_amdgcn_s_barrier()
;     __device__ void init(int M, int N, int G_, int c_) { base.init(M, N, G_, c_); }
; #define P_IN(i) ((const float*)rd_ptr(i))
; template <class Epi, class Sched, bool ALIGN_EPI = false, bool SP2 = false>
; __device__ __forceinline__ void gemm_phase(PG8_LAS unsigned char* lds, const Gemm g, const Sched& S, const Epi& E) {
;     ...
;         PG8_STAGE(PG8_SB(0, 0), cB, voffB); PG8_STAGE(PG8_SB(0, 1), cB + hstep, voffB); PG8_STAGE(PG8_SA(0, 0), cA, voffA); PG8_STAGE(PG8_SA(0, 1), cA + hstep, voffA);
;         if (wr == 1) PG8_BAR;
;         PG8_WAIT_V(2); PG8_BAR;
;         PG8_STAGE(PG8_SB(1, 0), cB + kstep, voffB); PG8_STAGE(PG8_SA(1, 0), cA + kstep, voffA); PG8_STAGE(PG8_SB(1, 1), cB + hstep + kstep, voffB);
;         PG8_WAIT_V(6); PG8_BAR;
; __global__ void __launch_bounds__(NTHR, 2) trunk_fwd(Args args) {
;     ...
;             pg8::Gemm g{(const u16*)(ws + WS_XB) + hrow * DM, (const u16*)(wl + WO_IN), MH, 24 * 256, DM}; pg8::StaticOrder S; S.init(MH, 24 * 256, G, bx);
;             pg8::EpiWin E{(u16*)(ws + WS_ZA), (u16*)(ws + WS_QC), (u16*)(ws + WS_KC), (u16*)(ws + WS_VC), (float*)(ws + WS_MIF), (const float*)(ws + WS_SSP) + hrow * 16, (const float*)(ws + WS_COS) + hrow * 32, (const float*)(ws + WS_SIN) + hrow * 32, P_IN(11) + l * 8};
.LBB0_1124:
	s_add_u32 s12, s62, 0xa400000
	s_addc_u32 s13, s63, 0
	s_add_u32 s28, s62, 0x17400000
	s_addc_u32 s52, s63, 0
	s_add_u32 s54, s62, 0x18400000
	s_addc_u32 s41, s63, 0
	s_add_u32 s14, s62, 0x1dc00000
	v_readlane_b32 s18, v255, 13
	s_addc_u32 s15, s63, 0
	s_lshl_b32 s1, s18, 6
	s_add_u32 s1, s62, s1
	s_addc_u32 s5, s63, 0
	s_add_u32 s16, s1, 0x1e500000
	s_addc_u32 s17, s5, 0
	s_lshl_b32 s1, s18, 7
	s_add_u32 s1, s62, s1
	s_addc_u32 s5, s63, 0
	v_readlane_b32 s19, v255, 14
	s_add_u32 s18, s1, 0x1dd00000
	s_addc_u32 s19, s5, 0
	s_add_u32 s20, s1, 0x1e100000
	s_addc_u32 s21, s5, 0
	s_lshl_b32 s30, s78, 3
	s_lshl_b64 s[50:51], s[30:31], 2
	s_add_u32 s66, s22, s50
	s_addc_u32 s67, s3, s51
	s_and_b32 s51, s23, 3
	s_lshl_b32 s1, s0, 6
	s_lshl_b32 s3, s0, 13
	s_lshl_b32 s68, s51, 5
	s_lshl_b32 s5, s51, 12
	global_load_dwordx4 v[248:251], v221, s[66:67]
	global_load_dwordx2 v[252:253], v221, s[66:67] offset:16
	global_load_dwordx2 v[232:233], v221, s[66:67] offset:24
	s_add_u32 s0, s10, 0x8000
	v_mov_b32_e32 v171, v221
	v_writelane_b32 v255, s1, 18
	s_addc_u32 s1, s11, 0
	s_add_i32 m0, s33, 0x18000
	v_lshl_add_u64 v[8:9], s[0:1], 0, v[170:171]
	v_mov_b32_e32 v175, v221
	s_waitcnt vmcnt(2)
	s_barrier
	global_load_lds_dwordx4 v[8:9], off
	s_add_i32 m0, s33, 0x1a000
	v_lshl_add_u64 v[8:9], s[0:1], 0, v[174:175]
	s_add_u32 s0, s6, 0x8000
	v_mov_b32_e32 v169, v221
	s_addc_u32 s1, s7, 0
	s_add_i32 s53, s33, 0x8000
	v_mov_b32_e32 v173, v221
	global_load_lds_dwordx4 v[8:9], off
	s_mov_b32 m0, s53
	s_add_i32 s27, s33, 0xa000
	global_load_lds_dwordx4 v168, s[0:1]
	v_lshl_add_u64 v[8:9], s[0:1], 0, v[172:173]
	s_add_u32 s0, s10, 0xc000
	s_mov_b32 m0, s27
	s_addc_u32 s1, s11, 0
	global_load_lds_dwordx4 v[8:9], off
	s_add_i32 m0, s33, 0x1c000
	s_nop 0
	global_load_lds_dwordx4 v170, s[0:1]
	s_add_i32 m0, s33, 0x1e000
	v_and_b32_e32 v7, 48, v0
	global_load_lds_dwordx4 v174, s[0:1]
	v_lshlrev_b32_e32 v8, 6, v0
	s_movk_i32 s0, 0x3c0
	v_lshlrev_b32_e32 v0, 2, v0
	s_cmpk_lt_u32 s2, 0x100
	v_and_or_b32 v7, v8, s0, v7
	v_and_b32_e32 v0, 32, v0
	s_cselect_b64 s[70:71], -1, 0
	s_lshl_b32 s0, s23, 11
	v_bitop3_b32 v8, v7, s3, v0 bitop3:0xde
	v_bitop3_b32 v192, v7, s5, v0 bitop3:0xde
	s_and_b32 s0, s0, 0x1000
	v_lshlrev_b32_e32 v0, 10, v1
	s_or_b32 s0, s0, 0xfffdc000
	v_and_b32_e32 v0, 0xfffff800, v0
	s_cmp_eq_u32 s51, 0
	v_lshl_add_u32 v0, v2, 7, v0
	v_and_b32_e32 v1, 1, v1
	s_cselect_b64 s[72:73], -1, 0
	s_lshl_b32 s2, s23, 6
	v_lshl_or_b32 v0, v1, 6, v0
	s_ashr_i32 s39, s60, 31
	s_ashr_i32 s50, s58, 31
	s_and_b32 s2, s2, 64
	v_lshl_add_u32 v176, v3, 1, v0
	v_lshlrev_b32_e32 v0, 10, v4
	s_add_u32 s2, s62, s2
	v_and_b32_e32 v0, 0xfffff800, v0
	s_waitcnt vmcnt(6)
	s_addc_u32 s3, s63, 0
	v_lshl_add_u32 v0, v5, 7, v0
	v_and_b32_e32 v1, 1, v4
	s_add_u32 s74, s2, 0x19400000
	v_lshl_or_b32 v0, v1, 6, v0
	s_mov_b32 s69, s31
	s_mov_b32 s1, 0
	s_addc_u32 s75, s3, 0
	v_mov_b32_e32 v177, v221
	v_lshl_add_u32 v178, v6, 1, v0
	v_mov_b32_e32 v179, v221
	v_add_u32_e32 v193, 0, v8
	s_barrier
	s_branch .LBB0_1127

;     __device__ __forceinline__ void operator()(const f32x4 (&acc)[2][2][4][2], const Unit& u, int wr, int wc, int, int) const {
;     ...
;                     if (wc == 0 && fq == 0) {
;                         float* mo = mif + (size_t)row * 8;
;                         *(v4f*)(mo) = (v4f){v0[0] + gate_b[0], v0[1] + gate_b[1], v0[2] + gate_b[2], v0[3] + gate_b[3]};
;                         *(v4f*)(mo + 4) = (v4f){v0[4] + gate_b[4], v0[5] + gate_b[5], v0[6] + gate_b[6], v0[7] + gate_b[7]};
;                     }
.LBB0_1148:
	s_andn2_b64 vcc, exec, s[10:11]
	s_cbranch_vccnz .LBB0_1152
	s_and_saveexec_b64 s[10:11], s[84:85]
	s_cbranch_execz .LBB0_1151
	s_nop 1
	v_lshlrev_b64 v[144:145], 5, v[180:181]
	v_lshl_add_u64 v[144:145], s[14:15], 0, v[144:145]
	v_pk_add_f32 v[196:197], v[166:167], v[248:249]
	v_pk_add_f32 v[198:199], v[158:159], v[250:251]
	global_store_dwordx4 v[144:145], v[196:199], off
	s_nop 1
	v_pk_add_f32 v[196:197], v[152:153], v[252:253]
	v_pk_add_f32 v[198:199], v[148:149], v[232:233]
	global_store_dwordx4 v[144:145], v[196:199], off offset:16

;     __device__ __forceinline__ void operator()(const f32x4 (&acc)[2][2][4][2], const Unit& u, int wr, int wc, int, int) const {
;     ...
;                     if (wc == 0 && fq == 0) {
;                         float* mo = mif + (size_t)row * 8;
;                         *(v4f*)(mo) = (v4f){v0[0] + gate_b[0], v0[1] + gate_b[1], v0[2] + gate_b[2], v0[3] + gate_b[3]};
;                         *(v4f*)(mo + 4) = (v4f){v0[4] + gate_b[4], v0[5] + gate_b[5], v0[6] + gate_b[6], v0[7] + gate_b[7]};
;                     }
.LBB0_1166:
	s_andn2_b64 vcc, exec, s[22:23]
	s_cbranch_vccnz .LBB0_1170
	s_and_saveexec_b64 s[94:95], s[84:85]
	s_cbranch_execz .LBB0_1169
	s_nop 1
	v_lshlrev_b64 v[152:153], 5, v[188:189]
	v_lshl_add_u64 v[152:153], s[14:15], 0, v[152:153]
	v_pk_add_f32 v[136:137], v[148:149], v[248:249]
	v_pk_add_f32 v[138:139], v[140:141], v[250:251]
	global_store_dwordx4 v[152:153], v[136:139], off
	s_nop 1
	v_pk_add_f32 v[136:137], v[132:133], v[252:253]
	v_pk_add_f32 v[138:139], v[128:129], v[232:233]
	global_store_dwordx4 v[152:153], v[136:139], off offset:16

;     __device__ __forceinline__ void operator()(const f32x4 (&acc)[2][2][4][2], const Unit& u, int wr, int wc, int, int) const {
;     ...
;                     if (wc == 0 && fq == 0) {
;                         float* mo = mif + (size_t)row * 8;
;                         *(v4f*)(mo) = (v4f){v0[0] + gate_b[0], v0[1] + gate_b[1], v0[2] + gate_b[2], v0[3] + gate_b[3]};
;                         *(v4f*)(mo + 4) = (v4f){v0[4] + gate_b[4], v0[5] + gate_b[5], v0[6] + gate_b[6], v0[7] + gate_b[7]};
;                     }
.LBB0_1188:
	s_andn2_b64 vcc, exec, s[22:23]
	s_cbranch_vccnz .LBB0_1192
	s_and_saveexec_b64 s[94:95], s[84:85]
	s_cbranch_execz .LBB0_1191
	s_nop 1
	v_lshlrev_b64 v[120:121], 5, v[138:139]
	v_lshl_add_u64 v[120:121], s[14:15], 0, v[120:121]
	v_pk_add_f32 v[138:139], v[132:133], v[248:249]
	v_pk_add_f32 v[140:141], v[124:125], v[250:251]
	global_store_dwordx4 v[120:121], v[138:141], off
	s_nop 1
	v_pk_add_f32 v[138:139], v[116:117], v[252:253]
	v_pk_add_f32 v[140:141], v[112:113], v[232:233]
	global_store_dwordx4 v[120:121], v[138:141], off offset:16

;     __device__ __forceinline__ void operator()(const f32x4 (&acc)[2][2][4][2], const Unit& u, int wr, int wc, int, int) const {
;     ...
;                     if (wc == 0 && fq == 0) {
;                         float* mo = mif + (size_t)row * 8;
;                         *(v4f*)(mo) = (v4f){v0[0] + gate_b[0], v0[1] + gate_b[1], v0[2] + gate_b[2], v0[3] + gate_b[3]};
;                         *(v4f*)(mo + 4) = (v4f){v0[4] + gate_b[4], v0[5] + gate_b[5], v0[6] + gate_b[6], v0[7] + gate_b[7]};
;                     }
.LBB0_1206:
	s_andn2_b64 vcc, exec, s[22:23]
	s_cbranch_vccnz .LBB0_1210
	s_and_saveexec_b64 s[94:95], s[84:85]
	s_cbranch_execz .LBB0_1209
	s_nop 1
	v_lshlrev_b64 v[118:119], 5, v[136:137]
	v_lshl_add_u64 v[118:119], s[14:15], 0, v[118:119]
	v_pk_add_f32 v[104:105], v[112:113], v[248:249]
	v_pk_add_f32 v[106:107], v[108:109], v[250:251]
	global_store_dwordx4 v[118:119], v[104:107], off
	s_nop 1
	v_pk_add_f32 v[104:105], v[100:101], v[252:253]
	v_pk_add_f32 v[106:107], v[96:97], v[232:233]
	global_store_dwordx4 v[118:119], v[104:107], off offset:16

;     __device__ __forceinline__ void operator()(const f32x4 (&acc)[2][2][4][2], const Unit& u, int wr, int wc, int, int) const {
;     ...
;                     if (wc == 0 && fq == 0) {
;                         float* mo = mif + (size_t)row * 8;
;                         *(v4f*)(mo) = (v4f){v0[0] + gate_b[0], v0[1] + gate_b[1], v0[2] + gate_b[2], v0[3] + gate_b[3]};
;                         *(v4f*)(mo + 4) = (v4f){v0[4] + gate_b[4], v0[5] + gate_b[5], v0[6] + gate_b[6], v0[7] + gate_b[7]};
;                     }
.LBB0_1228:
	s_andn2_b64 vcc, exec, s[22:23]
	s_cbranch_vccnz .LBB0_1232
	s_and_saveexec_b64 s[94:95], s[84:85]
	s_cbranch_execz .LBB0_1231
	s_nop 1
	v_lshlrev_b64 v[88:89], 5, v[106:107]
	v_lshl_add_u64 v[88:89], s[14:15], 0, v[88:89]
	v_pk_add_f32 v[110:111], v[100:101], v[248:249]
	v_pk_add_f32 v[112:113], v[92:93], v[250:251]
	global_store_dwordx4 v[88:89], v[110:113], off
	s_nop 1
	v_pk_add_f32 v[110:111], v[84:85], v[252:253]
	v_pk_add_f32 v[112:113], v[80:81], v[232:233]
	global_store_dwordx4 v[88:89], v[110:113], off offset:16

;     __device__ __forceinline__ void operator()(const f32x4 (&acc)[2][2][4][2], const Unit& u, int wr, int wc, int, int) const {
;     ...
;                     if (wc == 0 && fq == 0) {
;                         float* mo = mif + (size_t)row * 8;
;                         *(v4f*)(mo) = (v4f){v0[0] + gate_b[0], v0[1] + gate_b[1], v0[2] + gate_b[2], v0[3] + gate_b[3]};
;                         *(v4f*)(mo + 4) = (v4f){v0[4] + gate_b[4], v0[5] + gate_b[5], v0[6] + gate_b[6], v0[7] + gate_b[7]};
;                     }
.LBB0_1246:
	s_andn2_b64 vcc, exec, s[22:23]
	s_cbranch_vccnz .LBB0_1250
	s_and_saveexec_b64 s[94:95], s[84:85]
	s_cbranch_execz .LBB0_1249
	s_nop 1
	v_lshlrev_b64 v[86:87], 5, v[104:105]
	v_lshl_add_u64 v[86:87], s[14:15], 0, v[86:87]
	v_pk_add_f32 v[72:73], v[80:81], v[248:249]
	v_pk_add_f32 v[74:75], v[76:77], v[250:251]
	global_store_dwordx4 v[86:87], v[72:75], off
	s_nop 1
	v_pk_add_f32 v[72:73], v[68:69], v[252:253]
	v_pk_add_f32 v[74:75], v[64:65], v[232:233]
	global_store_dwordx4 v[86:87], v[72:75], off offset:16

;     __device__ __forceinline__ void operator()(const f32x4 (&acc)[2][2][4][2], const Unit& u, int wr, int wc, int, int) const {
;     ...
;                     if (wc == 0 && fq == 0) {
;                         float* mo = mif + (size_t)row * 8;
;                         *(v4f*)(mo) = (v4f){v0[0] + gate_b[0], v0[1] + gate_b[1], v0[2] + gate_b[2], v0[3] + gate_b[3]};
;                         *(v4f*)(mo + 4) = (v4f){v0[4] + gate_b[4], v0[5] + gate_b[5], v0[6] + gate_b[6], v0[7] + gate_b[7]};
;                     }
.LBB0_1268:
	s_andn2_b64 vcc, exec, s[6:7]
	s_cbranch_vccnz .LBB0_1272
	s_and_saveexec_b64 s[6:7], s[84:85]
	s_cbranch_execz .LBB0_1271
	s_nop 1
	v_lshlrev_b64 v[40:41], 5, v[74:75]
	v_lshl_add_u64 v[40:41], s[14:15], 0, v[40:41]
	v_pk_add_f32 v[74:75], v[68:69], v[248:249]
	v_pk_add_f32 v[76:77], v[44:45], v[250:251]
	global_store_dwordx4 v[40:41], v[74:77], off
	s_nop 1
	v_pk_add_f32 v[74:75], v[36:37], v[252:253]
	v_pk_add_f32 v[76:77], v[28:29], v[232:233]
	global_store_dwordx4 v[40:41], v[74:77], off offset:16

;     __device__ __forceinline__ void operator()(const f32x4 (&acc)[2][2][4][2], const Unit& u, int wr, int wc, int, int) const {
;     ...
;                     if (wc == 0 && fq == 0) {
;                         float* mo = mif + (size_t)row * 8;
;                         *(v4f*)(mo) = (v4f){v0[0] + gate_b[0], v0[1] + gate_b[1], v0[2] + gate_b[2], v0[3] + gate_b[3]};
;                         *(v4f*)(mo + 4) = (v4f){v0[4] + gate_b[4], v0[5] + gate_b[5], v0[6] + gate_b[6], v0[7] + gate_b[7]};
;                     }
.LBB0_1286:
	s_andn2_b64 vcc, exec, s[6:7]
	s_cbranch_vccnz .LBB0_1290
	s_and_saveexec_b64 s[6:7], s[84:85]
	s_cbranch_execz .LBB0_1289
	s_nop 1
	v_lshlrev_b64 v[38:39], 5, v[72:73]
	v_lshl_add_u64 v[38:39], s[14:15], 0, v[38:39]
	v_pk_add_f32 v[8:9], v[28:29], v[248:249]
	v_pk_add_f32 v[10:11], v[12:13], v[250:251]
	global_store_dwordx4 v[38:39], v[8:11], off
	s_nop 1
	v_pk_add_f32 v[8:9], v[4:5], v[252:253]
	v_pk_add_f32 v[10:11], v[0:1], v[232:233]
	global_store_dwordx4 v[38:39], v[8:11], off offset:16
